# gMLP path inside one XCD: each gMLP workgroup takes a token chunk of a block on its own XCD; G-tile stores and the gMLP o-column stores as plain L2 write-back stores
# speedup vs baseline: 1.0121x; 1.0036x over previous
.LBB0_1013:
	s_or_b64 exec, exec, s[4:5]
	s_and_b32 s7, s2, 7
	s_lshl_b32 s7, s7, 1
	s_bfe_u32 s6, s2, 0x20004
	s_lshl_b32 s6, s6, 4
	s_or_b32 s7, s7, s6
	s_bfe_u32 s6, s2, 0x10003
	s_or_b32 s7, s7, s6
	s_lshl_b32 s7, s7, 7
	v_or_b32_e32 v0, s7, v128
	v_ashrrev_i32_e32 v1, 31, v0
	v_lshlrev_b64 v[80:81], 10, v[0:1]
	v_or_b32_e32 v0, 64, v0
	v_ashrrev_i32_e32 v1, 31, v0
	v_lshlrev_b64 v[82:83], 10, v[0:1]
	v_lshrrev_b32_e32 v1, 4, v128
	s_add_i32 s6, s71, 0
	v_and_b32_e32 v85, 15, v166
	v_lshlrev_b32_e32 v0, 3, v1
	v_lshlrev_b32_e32 v84, 2, v1
	v_and_b32_e32 v1, 48, v166
	v_or_b32_e32 v3, 48, v128
	v_add_u32_e32 v1, s6, v1
	v_mul_u32_u24_e32 v2, 0x110, v85
	v_mul_u32_u24_e32 v3, 0x110, v3
	v_cmp_eq_u32_e64 s[4:5], 0, v128
	v_lshl_add_u32 v129, v128, 1, s6
	v_or_b32_e32 v167, s7, v85
	v_lshlrev_b32_e32 v144, 1, v0
	v_add_u32_e32 v168, v1, v2
	v_add_u32_e32 v169, v1, v3
	s_waitcnt lgkmcnt(0)
	s_barrier
	s_branch .LBB0_1015
